# v118 with the sparse split charging the K/V block load 7/8 of a tile (was 6/8)
# speedup vs baseline: 1.0033x; 1.0033x over previous
.LBB0_789:
	s_or_b64 exec, exec, s[4:5]
	v_and_b32_e32 v1, 63, v0
	s_cmp_lt_u32 s33, 64
	v_and_b32_e32 v7, 64, v6
	v_cmp_gt_u32_e32 vcc, 32, v1
	s_waitcnt lgkmcnt(0)
	s_barrier
	s_cbranch_scc0 .LBB0_793
	v_lshlrev_b32_e32 v20, 6, v1
	v_add_u32_e32 v2, 0, v20
	v_add_u32_e32 v16, 0x20400, v2
	ds_read_b128 v[2:5], v16
	s_movk_i32 s6, 0xff
	ds_read_b128 v[8:11], v16 offset:16
	ds_read_b128 v[12:15], v16 offset:32
	ds_read_b128 v[16:19], v16 offset:48
	v_add_u32_e32 v38, -2, v6
	s_add_i32 s16, 0, 0x21400
	s_waitcnt lgkmcnt(3)
	v_add_u32_e32 v2, 0xff, v2
	v_add_u32_e32 v3, 0xff, v3
	v_lshrrev_b32_e32 v24, 8, v2
	v_lshl_add_u32 v24, v24, 3, 7
	v_lshrrev_b32_e32 v23, 8, v3
	v_lshl_add_u32 v23, v23, 3, 7
	v_cmp_lt_u32_e64 s[4:5], s6, v2
	v_lshrrev_b32_e32 v21, 8, v2
	v_cndmask_b32_e64 v24, 0, v24, s[4:5]
	v_cmp_lt_u32_e64 s[4:5], s6, v3
	v_lshrrev_b32_e32 v22, 8, v3
	s_waitcnt lgkmcnt(2)
	v_add_u32_e32 v8, 0xff, v8
	v_cndmask_b32_e64 v2, 0, v23, s[4:5]
	v_add_u32_e32 v23, v2, v24
	v_add_u32_e32 v2, 0xff, v4
	v_lshrrev_b32_e32 v4, 8, v2
	v_lshl_add_u32 v4, v4, 3, 7
	v_cmp_lt_u32_e64 s[4:5], s6, v2
	v_lshrrev_b32_e32 v3, 8, v2
	v_lshrrev_b32_e32 v26, 8, v8
	v_lshl_add_u32 v26, v26, 3, 7
	v_cndmask_b32_e64 v2, 0, v4, s[4:5]
	v_add_u32_e32 v4, 0xff, v5
	v_lshrrev_b32_e32 v25, 8, v4
	v_lshl_add_u32 v25, v25, 3, 7
	v_cmp_lt_u32_e64 s[4:5], s6, v4
	v_add_u32_e32 v9, 0xff, v9
	v_lshrrev_b32_e32 v5, 8, v4
	v_cndmask_b32_e64 v4, 0, v25, s[4:5]
	v_cmp_lt_u32_e64 s[4:5], s6, v8
	v_lshrrev_b32_e32 v27, 8, v9
	v_lshl_add_u32 v27, v27, 3, 7
	v_add_u32_e32 v10, 0xff, v10
	v_add_u32_e32 v22, v22, v21
	v_lshrrev_b32_e32 v25, 8, v8
	v_cndmask_b32_e64 v8, 0, v26, s[4:5]
	v_cmp_lt_u32_e64 s[4:5], s6, v9
	v_lshrrev_b32_e32 v28, 8, v10
	v_lshl_add_u32 v28, v28, 3, 7
	v_add_u32_e32 v11, 0xff, v11
	v_lshrrev_b32_e32 v26, 8, v9
	v_cndmask_b32_e64 v9, 0, v27, s[4:5]
	v_cmp_lt_u32_e64 s[4:5], s6, v10
	v_lshrrev_b32_e32 v29, 8, v11
	v_lshl_add_u32 v29, v29, 3, 7
	s_waitcnt lgkmcnt(1)
	v_add_u32_e32 v12, 0xff, v12
	v_add_u32_e32 v3, v3, v22
	v_lshrrev_b32_e32 v27, 8, v10
	v_cndmask_b32_e64 v10, 0, v28, s[4:5]
	v_cmp_lt_u32_e64 s[4:5], s6, v11
	v_lshrrev_b32_e32 v30, 8, v12
	v_lshl_add_u32 v30, v30, 3, 7
	v_add_u32_e32 v13, 0xff, v13
	v_add_u32_e32 v5, v5, v3
	v_lshrrev_b32_e32 v28, 8, v11
	v_cndmask_b32_e64 v11, 0, v29, s[4:5]
	v_cmp_lt_u32_e64 s[4:5], s6, v12
	v_lshrrev_b32_e32 v31, 8, v13
	v_lshl_add_u32 v31, v31, 3, 7
	v_add_u32_e32 v14, 0xff, v14
	v_add_u32_e32 v25, v25, v5
	v_lshrrev_b32_e32 v29, 8, v12
	v_cndmask_b32_e64 v12, 0, v30, s[4:5]
	v_cmp_lt_u32_e64 s[4:5], s6, v13
	v_lshrrev_b32_e32 v32, 8, v14
	v_lshl_add_u32 v32, v32, 3, 7
	v_add_u32_e32 v15, 0xff, v15
	v_add_u32_e32 v26, v26, v25
	v_lshrrev_b32_e32 v30, 8, v13
	v_cndmask_b32_e64 v13, 0, v31, s[4:5]
	v_cmp_lt_u32_e64 s[4:5], s6, v14
	v_lshrrev_b32_e32 v33, 8, v15
	v_lshl_add_u32 v33, v33, 3, 7
	s_waitcnt lgkmcnt(0)
	v_add_u32_e32 v16, 0xff, v16
	v_add_u32_e32 v27, v27, v26
	v_lshrrev_b32_e32 v31, 8, v14
	v_cndmask_b32_e64 v14, 0, v32, s[4:5]
	v_cmp_lt_u32_e64 s[4:5], s6, v15
	v_lshrrev_b32_e32 v34, 8, v16
	v_lshl_add_u32 v34, v34, 3, 7
	v_add_u32_e32 v17, 0xff, v17
	v_add_u32_e32 v28, v28, v27
	v_lshrrev_b32_e32 v32, 8, v15
	v_cndmask_b32_e64 v15, 0, v33, s[4:5]
	v_cmp_lt_u32_e64 s[4:5], s6, v16
	v_lshrrev_b32_e32 v35, 8, v17
	v_lshl_add_u32 v35, v35, 3, 7
	v_add_u32_e32 v18, 0xff, v18
	v_add_u32_e32 v29, v29, v28
	v_lshrrev_b32_e32 v33, 8, v16
	v_cndmask_b32_e64 v16, 0, v34, s[4:5]
	v_cmp_lt_u32_e64 s[4:5], s6, v17
	v_lshrrev_b32_e32 v36, 8, v18
	v_lshl_add_u32 v36, v36, 3, 7
	v_add_u32_e32 v19, 0xff, v19
	v_add_u32_e32 v30, v30, v29
	v_lshrrev_b32_e32 v34, 8, v17
	v_cndmask_b32_e64 v17, 0, v35, s[4:5]
	v_cmp_lt_u32_e64 s[4:5], s6, v18
	v_lshrrev_b32_e32 v37, 8, v19
	v_lshl_add_u32 v37, v37, 3, 7
	v_add_u32_e32 v31, v31, v30
	v_lshrrev_b32_e32 v35, 8, v18
	v_cndmask_b32_e64 v18, 0, v36, s[4:5]
	v_cmp_lt_u32_e64 s[4:5], s6, v19
	v_add_u32_e32 v32, v32, v31
	v_lshrrev_b32_e32 v36, 8, v19
	v_cndmask_b32_e64 v19, 0, v37, s[4:5]
	v_add_u32_e32 v37, -1, v6
	v_add_u32_e32 v33, v33, v32
	v_cmp_lt_i32_e64 s[4:5], v37, v7
	v_add_u32_e32 v47, v2, v23
	v_add_u32_e32 v34, v34, v33
	v_cndmask_b32_e64 v37, v37, v6, s[4:5]
	s_add_i32 s17, 0, 0x22800
	v_add_u32_e32 v4, v4, v47
	v_or_b32_e32 v2, 20, v20
	v_add_u32_e32 v35, v35, v34
	v_lshlrev_b32_e32 v37, 2, v37
	v_cmp_lt_i32_e64 s[4:5], v38, v7
	v_add_u32_e32 v39, -4, v6
	v_add_u32_e32 v48, s16, v2
	v_add_u32_e32 v49, s17, v2
	v_add_u32_e32 v50, v8, v4
	v_or_b32_e32 v2, 28, v20
	v_add_u32_e32 v8, v36, v35
	v_cndmask_b32_e64 v38, v38, v6, s[4:5]
	v_cmp_lt_i32_e64 s[4:5], v39, v7
	v_add_u32_e32 v40, -8, v6
	v_add_u32_e32 v52, s16, v2
	v_add_u32_e32 v53, s17, v2
	ds_bpermute_b32 v2, v37, v8
	v_cndmask_b32_e64 v39, v39, v6, s[4:5]
	v_cmp_lt_i32_e64 s[4:5], v40, v7
	v_add_u32_e32 v41, -16, v6
	v_subrev_u32_e32 v42, 32, v6
	v_cndmask_b32_e64 v40, v40, v6, s[4:5]
	v_cmp_lt_i32_e64 s[4:5], v41, v7
	v_lshlrev_b32_e32 v38, 2, v38
	v_add_u32_e32 v51, v9, v50
	v_cndmask_b32_e64 v41, v41, v6, s[4:5]
	v_cmp_lt_i32_e64 s[4:5], v42, v7
	v_add_u32_e32 v36, v10, v51
	v_or_b32_e32 v9, 36, v20
	v_cndmask_b32_e64 v42, v42, v6, s[4:5]
	v_cmp_eq_u32_e64 s[4:5], 0, v1
	v_cmp_gt_u32_e64 s[6:7], 2, v1
	v_add_u32_e32 v54, v11, v36
	s_waitcnt lgkmcnt(0)
	v_cndmask_b32_e64 v2, v2, 0, s[4:5]
	v_add_u32_e32 v2, v8, v2
	ds_bpermute_b32 v10, v38, v2
	v_add_u32_e32 v11, s16, v9
	v_add_u32_e32 v55, s17, v9
	v_lshlrev_b32_e32 v39, 2, v39
	v_cmp_gt_u32_e64 s[8:9], 4, v1
	s_waitcnt lgkmcnt(0)
	v_cndmask_b32_e64 v9, v10, 0, s[6:7]
	v_add_u32_e32 v2, v2, v9
	ds_bpermute_b32 v9, v39, v2
	v_lshlrev_b32_e32 v40, 2, v40
	v_cmp_gt_u32_e64 s[10:11], 8, v1
	v_lshlrev_b32_e32 v41, 2, v41
	v_add_u32_e32 v56, v12, v54
	s_waitcnt lgkmcnt(0)
	v_cndmask_b32_e64 v9, v9, 0, s[8:9]
	v_add_u32_e32 v2, v9, v2
	ds_bpermute_b32 v9, v40, v2
	v_add_u32_e32 v13, v13, v56
	v_add_u32_e32 v14, v14, v13
	v_add_u32_e32 v15, v15, v14
	v_cmp_gt_u32_e64 s[12:13], 16, v1
	s_waitcnt lgkmcnt(0)
	v_cndmask_b32_e64 v9, v9, 0, s[10:11]
	v_add_u32_e32 v2, v9, v2
	ds_bpermute_b32 v9, v41, v2
	v_add_u32_e32 v16, v16, v15
	v_lshlrev_b32_e32 v42, 2, v42
	v_add_u32_e32 v17, v17, v16
	v_add_u32_e32 v18, v18, v17
	s_waitcnt lgkmcnt(0)
	v_cndmask_b32_e64 v9, v9, 0, s[12:13]
	v_add_u32_e32 v2, v9, v2
	ds_bpermute_b32 v9, v42, v2
	v_add_u32_e32 v19, v19, v18
	ds_bpermute_b32 v37, v37, v19
	v_or_b32_e32 v10, 44, v20
	v_add_u32_e32 v12, s16, v10
	s_waitcnt lgkmcnt(1)
	v_cndmask_b32_e64 v9, v9, 0, vcc
	v_add_u32_e32 v2, v9, v2
	v_add_u32_e32 v57, s17, v10
	v_or_b32_e32 v10, 52, v20
	v_sub_u32_e32 v8, v2, v8
	s_waitcnt lgkmcnt(0)
	v_cndmask_b32_e64 v9, v37, 0, s[4:5]
	v_add_u32_e32 v58, s16, v10
	v_add_u32_e32 v59, s17, v10
	v_add_u32_e32 v10, v8, v22
	v_add_u32_e32 v22, v19, v9
	ds_bpermute_b32 v37, v38, v22
	v_add_u32_e32 v43, s16, v20
	v_add_u32_e32 v9, v8, v21
	ds_write_b96 v43, v[8:10]
	v_or_b32_e32 v45, 12, v20
	s_waitcnt lgkmcnt(1)
	v_cndmask_b32_e64 v9, v37, 0, s[6:7]
	v_add_u32_e32 v9, v22, v9
	ds_bpermute_b32 v10, v39, v9
	v_add_u32_e32 v46, s16, v45
	v_add_u32_e32 v5, v8, v5
	v_add_u32_e32 v3, v8, v3
	ds_write2_b32 v46, v3, v5 offset1:1
	v_add_u32_e32 v3, v8, v26
	v_add_u32_e32 v5, v8, v25
	ds_write2_b32 v48, v5, v3 offset1:1
	s_waitcnt lgkmcnt(2)
	v_cndmask_b32_e64 v3, v10, 0, s[8:9]
	v_add_u32_e32 v3, v9, v3
	ds_bpermute_b32 v5, v40, v3
	v_add_u32_e32 v9, v8, v28
	v_add_u32_e32 v10, v8, v27
	ds_write2_b32 v52, v10, v9 offset1:1
	v_add_u32_e32 v9, v8, v30
	s_waitcnt lgkmcnt(1)
	v_cndmask_b32_e64 v5, v5, 0, s[10:11]
	v_add_u32_e32 v3, v3, v5
	ds_bpermute_b32 v5, v41, v3
	v_add_u32_e32 v10, v8, v29
	ds_write2_b32 v11, v10, v9 offset1:1
	v_add_u32_e32 v9, v8, v32
	v_add_u32_e32 v10, v8, v31
	s_waitcnt lgkmcnt(1)
	v_cndmask_b32_e64 v5, v5, 0, s[12:13]
	v_add_u32_e32 v3, v5, v3
	ds_bpermute_b32 v5, v42, v3
	ds_write2_b32 v12, v10, v9 offset1:1
	v_add_u32_e32 v9, v8, v34
	v_add_u32_e32 v10, v8, v33
	ds_write2_b32 v58, v10, v9 offset1:1
	s_waitcnt lgkmcnt(2)
	v_cndmask_b32_e64 v5, v5, 0, vcc
	v_add_u32_e32 v3, v5, v3
	v_sub_u32_e32 v10, v3, v19
	v_add_u32_e32 v45, s17, v45
	v_add_u32_e32 v4, v10, v4
	v_add_u32_e32 v5, v10, v47
	ds_write2_b32 v45, v5, v4 offset1:1
	v_add_u32_e32 v4, v10, v51
	v_add_u32_e32 v5, v10, v50
	ds_write2_b32 v49, v5, v4 offset1:1
	v_add_u32_e32 v4, v10, v54
	v_add_u32_e32 v5, v10, v36
	ds_write2_b32 v53, v5, v4 offset1:1
	v_add_u32_e32 v4, v10, v13
	v_add_u32_e32 v5, v10, v56
	ds_write2_b32 v55, v5, v4 offset1:1
	v_add_u32_e32 v4, v10, v15
	v_add_u32_e32 v5, v10, v14
	ds_write2_b32 v57, v5, v4 offset1:1
	v_add_u32_e32 v4, v10, v17
	v_add_u32_e32 v5, v10, v16
	ds_write2_b32 v59, v5, v4 offset1:1
	v_or_b32_e32 v5, 60, v20
	v_add_u32_e32 v4, v8, v35
	v_add_u32_e32 v8, s16, v5
	v_add_u32_e32 v44, s17, v20
	v_add_u32_e32 v12, v10, v23
	v_add_u32_e32 v11, v10, v24
	ds_write_b32 v8, v4
	v_add_u32_e32 v4, v10, v18
	v_add_u32_e32 v5, s17, v5
	v_cmp_eq_u32_e32 vcc, 63, v1
	ds_write_b96 v44, v[10:12]
	ds_write_b32 v5, v4
	s_and_saveexec_b64 s[4:5], vcc
	s_cbranch_execz .LBB0_792
	s_add_i32 s6, 0, 0x22400
	v_mov_b32_e32 v4, s6
	s_add_i32 s6, 0, 0x23800
	ds_write_b32 v4, v2
	v_mov_b32_e32 v2, s6
	ds_write_b32 v2, v3

.LBB0_798:
	v_mbcnt_lo_u32_b32 v60, -1, 0
	v_mbcnt_hi_u32_b32 v60, -1, v60
	v_lshlrev_b32_e32 v61, 6, v60
	v_add_u32_e32 v61, 0x2283c, v61
	ds_read_b32 v61, v61
	s_waitcnt lgkmcnt(0)
	v_cmp_ge_u32_e64 s[100:101], s6, v61
	s_bcnt1_i32_b64 s99, s[100:101]
	s_min_u32 s99, s99, 63
	s_lshl_b32 s100, s99, 6
	v_lshl_add_u32 v61, v60, 2, s100
	v_add_u32_e32 v61, 0x22800, v61
	ds_read_b32 v61, v61
	s_waitcnt lgkmcnt(0)
	v_cmp_ge_u32_e64 s[100:101], s6, v61
	s_and_b32 s100, s100, 0xffff
	s_bcnt1_i32_b32 s100, s100
	s_lshl_b32 s4, s99, 4
	s_add_i32 s4, s4, s100
	s_add_i32 s4, s4, -1
	s_lshl_b32 s4, s4, 2
	s_add_i32 s4, s4, 0
	s_add_i32 s5, s4, 0x21400
	s_add_i32 s4, s4, 0x22800
	v_mov_b32_e32 v4, s5
	v_mov_b32_e32 v8, s4
	ds_read2_b32 v[4:5], v4 offset1:1
	ds_read_b32 v8, v8
	s_waitcnt lgkmcnt(1)
	v_readfirstlane_b32 s4, v4
	s_waitcnt lgkmcnt(0)
	v_readfirstlane_b32 s10, v8
	v_readfirstlane_b32 s5, v5
	s_add_i32 s11, s10, 7
	s_sub_i32 s10, s6, s10
	s_sub_i32 s7, s5, s4
	s_add_i32 s10, s10, 0
	s_lshr_b32 s10, s10, 3
	s_cmp_lt_u32 s11, s6
	s_cselect_b32 s6, s10, 0
	s_add_i32 s4, s6, s4
	s_cmp_lt_u32 s6, s7
	s_cselect_b32 s66, s4, s5

.LBB0_805:
	v_mbcnt_lo_u32_b32 v60, -1, 0
	v_mbcnt_hi_u32_b32 v60, -1, v60
	v_lshlrev_b32_e32 v61, 6, v60
	v_add_u32_e32 v61, 0x2283c, v61
	ds_read_b32 v61, v61
	s_waitcnt lgkmcnt(0)
	v_cmp_ge_u32_e64 s[100:101], s6, v61
	s_bcnt1_i32_b64 s99, s[100:101]
	s_min_u32 s99, s99, 63
	s_lshl_b32 s100, s99, 6
	v_lshl_add_u32 v61, v60, 2, s100
	v_add_u32_e32 v61, 0x22800, v61
	ds_read_b32 v61, v61
	s_waitcnt lgkmcnt(0)
	v_cmp_ge_u32_e64 s[100:101], s6, v61
	s_and_b32 s100, s100, 0xffff
	s_bcnt1_i32_b32 s100, s100
	s_lshl_b32 s4, s99, 4
	s_add_i32 s4, s4, s100
	s_add_i32 s4, s4, -1
	s_lshl_b32 s4, s4, 2
	s_add_i32 s4, s4, 0
	s_add_i32 s5, s4, 0x21400
	s_add_i32 s4, s4, 0x22800
	v_mov_b32_e32 v2, s5
	v_mov_b32_e32 v4, s4
	ds_read2_b32 v[2:3], v2 offset1:1
	ds_read_b32 v4, v4
	s_waitcnt lgkmcnt(1)
	v_sub_u32_e32 v5, v3, v2
	s_waitcnt lgkmcnt(0)
	v_add_u32_e32 v8, 7, v4
	v_sub_u32_e32 v4, s6, v4
	v_add_u32_e32 v4, 0, v4
	v_lshrrev_b32_e32 v4, 3, v4
	v_cmp_gt_u32_e32 vcc, s6, v8
	s_nop 1
	v_cndmask_b32_e32 v4, 0, v4, vcc
	v_add_u32_e32 v2, v4, v2
	v_cmp_lt_u32_e32 vcc, v4, v5
	s_nop 1
	v_cndmask_b32_e32 v186, v3, v2, vcc
